# operand warm-up: at the seam before P5 wave 3 reads the S5 tables of the workgroup's scan item (144 KiB) so the scan's item-begin loads hit the memory-side cache, stacked on v93
# baseline (speedup 1.0000x reference)
.Lcpf_skip_3:
	v_readlane_b32 s98, v254, 61
	s_cmp_lg_u32 s98, 3
	s_cbranch_scc1 .Lcpf_skip_tw
	v_lshlrev_b32_e32 v252, 7, v186
	v_readlane_b32 s98, v255, 10
	s_and_b32 s98, s98, 63
	s_lshl_b32 s98, s98, 16
	s_add_u32 s98, s98, 0x300000
	s_add_u32 s98, s70, s98
	s_addc_u32 s99, s71, 0
	global_load_dword v253, v252, s[98:99]
	s_add_u32 s98, s98, 0x2000
	s_addc_u32 s99, s99, 0
	global_load_dword v253, v252, s[98:99]
	s_add_u32 s98, s98, 0x2000
	s_addc_u32 s99, s99, 0
	global_load_dword v253, v252, s[98:99]
	s_add_u32 s98, s98, 0x2000
	s_addc_u32 s99, s99, 0
	global_load_dword v253, v252, s[98:99]
	s_add_u32 s98, s98, 0x2000
	s_addc_u32 s99, s99, 0
	global_load_dword v253, v252, s[98:99]
	s_add_u32 s98, s98, 0x2000
	s_addc_u32 s99, s99, 0
	global_load_dword v253, v252, s[98:99]
	s_add_u32 s98, s98, 0x2000
	s_addc_u32 s99, s99, 0
	global_load_dword v253, v252, s[98:99]
	s_add_u32 s98, s98, 0x2000
	s_addc_u32 s99, s99, 0
	global_load_dword v253, v252, s[98:99]
	v_readlane_b32 s98, v255, 10
	s_and_b32 s98, s98, 63
	s_lshl_b32 s98, s98, 16
	s_add_u32 s98, s98, 0x700000
	s_add_u32 s98, s70, s98
	s_addc_u32 s99, s71, 0
	global_load_dword v253, v252, s[98:99]
	s_add_u32 s98, s98, 0x2000
	s_addc_u32 s99, s99, 0
	global_load_dword v253, v252, s[98:99]
	s_add_u32 s98, s98, 0x2000
	s_addc_u32 s99, s99, 0
	global_load_dword v253, v252, s[98:99]
	s_add_u32 s98, s98, 0x2000
	s_addc_u32 s99, s99, 0
	global_load_dword v253, v252, s[98:99]
	s_add_u32 s98, s98, 0x2000
	s_addc_u32 s99, s99, 0
	global_load_dword v253, v252, s[98:99]
	s_add_u32 s98, s98, 0x2000
	s_addc_u32 s99, s99, 0
	global_load_dword v253, v252, s[98:99]
	s_add_u32 s98, s98, 0x2000
	s_addc_u32 s99, s99, 0
	global_load_dword v253, v252, s[98:99]
	s_add_u32 s98, s98, 0x2000
	s_addc_u32 s99, s99, 0
	global_load_dword v253, v252, s[98:99]
	v_readlane_b32 s98, v255, 10
	s_and_b32 s98, s98, 63
	s_lshl_b32 s98, s98, 14
	s_add_u32 s98, s98, 0xb00000
	s_add_u32 s98, s70, s98
	s_addc_u32 s99, s71, 0
	global_load_dword v253, v252, s[98:99]
	s_add_u32 s98, s98, 0x2000
	s_addc_u32 s99, s99, 0
	global_load_dword v253, v252, s[98:99]
